# NSA selected tile: partial row-max and 7 accumulator copies moved into the QK MFMA chain shadows
# baseline (speedup 1.0000x reference)
; DI float ex2(float x) { return __builtin_amdgcn_exp2f(x); }
; #define SB0 __builtin_amdgcn_sched_barrier(0)
; DI void nsa_S(f32x4 (&s)[4], const char* Kb, const char* Vb, const bf16x8 (&qf)[4], bf16x8 (&v0)[4], int lr, int quad) {
;   bf16x8 k0[4], k1[4], k2[4], k3[4];
;   ldk4(k0, Kb, 0, lr, quad); SB0;
;   ldk4(k1, Kb, 1, lr, quad); s[0] = mma4(k0, qf); SB0;
;   ldk4(k2, Kb, 2, lr, quad); s[1] = mma4(k1, qf); SB0;
;   ldk4(k3, Kb, 3, lr, quad); s[2] = mma4(k2, qf); SB0;
;   ldv4(v0, Vb, 0, lr, quad); s[3] = mma4(k3, qf); SB0;
; }
; template <bool MASKED, class MF>
; DI void flash_update(f32x4 (&s)[4], float scl, float& mx, float& ls, f32x4 (&o)[8], MF maskfn, bool lane_on) {
;   float tmax = -1e30f;
; #pragma unroll
;   for (int kt = 0; kt < 4; ++kt)
; #pragma unroll
;     for (int i = 0; i < 4; ++i) {
;       if (MASKED) { if (maskfn(kt, i)) s[kt][i] = -1e30f; }
;       tmax = fmaxf(tmax, s[kt][i]);
;     }
;   tmax = rowmax4(tmax);
;   if (!lane_on) tmax = -1e30f;
;   const float th = 8.f / scl;
;   if (__any(tmax > mx + th)) {
;     const float mnew = fmaxf(mx, tmax);
;     const float alpha = ex2((mx - mnew) * scl);
;     ls *= alpha;
; #pragma unroll
;     for (int dt = 0; dt < 8; ++dt) o[dt] *= alpha;
;     mx = mnew;
;   }
.LBB0_817:
	s_or_b32 s59, s48, s56
	s_cmp_gt_u32 s59, s2
	s_cbranch_scc1 .LBB0_816
	s_and_b32 s38, s59, 31
	s_waitcnt lgkmcnt(0)
	v_mov_b32_e32 v0, v172
	v_lshrrev_b32_e32 v1, s59, v0
	v_bfe_u32 v0, v0, s38, 1
	v_and_b32_e32 v1, 1, v1
	v_cmp_ne_u32_e32 vcc, 0, v0
	v_cmp_eq_u32_e64 s[38:39], 1, v1
	s_cbranch_vccz .LBB0_829
	s_lshl_b32 s48, s48, 15
	s_add_i32 s58, s57, s48
	v_add_u32_e32 v8, s58, v234
	v_add_u32_e32 v122, v8, v235
	v_add_u32_e32 v124, v8, v237
	v_add_u32_e32 v123, v8, v236
	ds_read_b128 v[0:3], v122
	ds_read_b128 v[4:7], v123
	v_add_u32_e32 v125, v8, v238
	ds_read_b128 v[8:11], v124
	ds_read_b128 v[12:15], v125
	ds_read_b128 v[98:101], v122 offset:4096
	ds_read_b128 v[102:105], v123 offset:4096
	ds_read_b128 v[106:109], v124 offset:4096
	ds_read_b128 v[110:113], v125 offset:4096
	s_waitcnt lgkmcnt(7)
	v_mfma_f32_16x16x32_bf16 v[142:145], v[0:3], v[18:21], 0
	s_waitcnt lgkmcnt(6)
	v_mfma_f32_16x16x32_bf16 v[142:145], v[4:7], v[22:25], v[142:145]
	s_waitcnt lgkmcnt(5)
	v_mfma_f32_16x16x32_bf16 v[142:145], v[8:11], v[26:29], v[142:145]
	s_waitcnt lgkmcnt(4)
	v_mfma_f32_16x16x32_bf16 v[114:117], v[12:15], v[30:33], v[142:145]
	ds_read_b128 v[0:3], v122 offset:8192
	ds_read_b128 v[4:7], v123 offset:8192
	ds_read_b128 v[8:11], v124 offset:8192
	ds_read_b128 v[12:15], v125 offset:8192
	s_waitcnt lgkmcnt(7)
	v_mfma_f32_16x16x32_bf16 v[98:101], v[98:101], v[18:21], 0
	s_waitcnt lgkmcnt(6)
	v_mfma_f32_16x16x32_bf16 v[98:101], v[102:105], v[22:25], v[98:101]
	s_waitcnt lgkmcnt(5)
	v_mfma_f32_16x16x32_bf16 v[98:101], v[106:109], v[26:29], v[98:101]
	s_waitcnt lgkmcnt(4)
	v_mfma_f32_16x16x32_bf16 v[118:121], v[110:113], v[30:33], v[98:101]
	v_max3_f32 v160, v114, s41, v115
	v_max3_f32 v160, v160, v116, v117
	v_mov_b64_e32 v[156:157], v[72:73]
	v_mov_b64_e32 v[152:153], v[76:77]
	v_mov_b64_e32 v[148:149], v[80:81]
	s_nop 0
	ds_read_b128 v[126:129], v122 offset:12288
	ds_read_b128 v[130:133], v123 offset:12288
	ds_read_b128 v[134:137], v124 offset:12288
	ds_read_b128 v[138:141], v125 offset:12288
	s_waitcnt lgkmcnt(7)
	v_mfma_f32_16x16x32_bf16 v[142:145], v[0:3], v[18:21], 0
	s_waitcnt lgkmcnt(6)
	v_mfma_f32_16x16x32_bf16 v[142:145], v[4:7], v[22:25], v[142:145]
	s_waitcnt lgkmcnt(5)
	v_mfma_f32_16x16x32_bf16 v[142:145], v[8:11], v[26:29], v[142:145]
	s_waitcnt lgkmcnt(4)
	v_mfma_f32_16x16x32_bf16 v[122:125], v[12:15], v[30:33], v[142:145]
	v_max3_f32 v160, v160, v118, v119
	v_max3_f32 v160, v160, v120, v121
	v_mov_b64_e32 v[158:159], v[66:67]
	v_mov_b64_e32 v[154:155], v[70:71]
	v_mov_b64_e32 v[150:151], v[74:75]
	v_add_u32_e32 v0, s58, v242
	v_add_u32_e32 v174, v0, v241
	ds_read_b128 v[98:101], v174 offset:16384
	ds_read_b128 v[102:105], v174 offset:18432
	ds_read_b128 v[106:109], v174 offset:20480
	ds_read_b128 v[110:113], v174 offset:22528
	s_waitcnt lgkmcnt(7)
	v_mfma_f32_16x16x32_bf16 v[0:3], v[126:129], v[18:21], 0
	s_waitcnt lgkmcnt(6)
	v_mfma_f32_16x16x32_bf16 v[0:3], v[130:133], v[22:25], v[0:3]
	s_waitcnt lgkmcnt(5)
	v_mfma_f32_16x16x32_bf16 v[0:3], v[134:137], v[26:29], v[0:3]
	s_waitcnt lgkmcnt(4)
	v_mfma_f32_16x16x32_bf16 v[126:129], v[138:141], v[30:33], v[0:3]
	v_max3_f32 v160, v160, v122, v123
	v_max3_f32 v160, v160, v124, v125
	v_mov_b64_e32 v[146:147], v[78:79]
	s_nop 0
	s_mov_b64 s[48:49], -1
	s_cmp_lg_u32 s59, s2
	v_add_f32_e32 v176, 0x427af232, v173
	s_cbranch_scc0 .LBB0_823
	v_mov_b64_e32 v[144:145], v[84:85]
	v_mov_b64_e32 v[140:141], v[88:89]
	v_max3_f32 v0, v160, v126, v127
	v_mov_b64_e32 v[160:161], v[68:69]
	v_max3_f32 v0, v0, v128, v129
	v_mov_b32_e32 v1, v0
	v_mov_b64_e32 v[136:137], v[92:93]
	v_mov_b64_e32 v[132:133], v[96:97]
	v_permlane16_swap_b32_e32 v0, v1
	v_max_f32_e32 v0, v0, v1
	v_mov_b32_e32 v1, v0
	v_mov_b64_e32 v[142:143], v[82:83]
	v_mov_b64_e32 v[138:139], v[86:87]
	v_permlane32_swap_b32_e32 v0, v1
	v_max_f32_e32 v0, v0, v1
	v_cndmask_b32_e64 v0, v231, v0, s[38:39]
	v_mov_b64_e32 v[134:135], v[90:91]
	v_mov_b64_e32 v[130:131], v[94:95]
	v_cmp_gt_f32_e32 vcc, v0, v176
	v_mov_b32_e32 v177, v170
	v_mov_b32_e32 v175, v173
	s_cbranch_vccz .LBB0_822
	v_max_f32_e32 v0, v0, v0
	v_max_f32_e32 v1, v173, v173
	v_max_f32_e32 v175, v1, v0
	v_sub_f32_e32 v0, v173, v175
	v_mul_f32_e32 v0, 0x3e0293ee, v0
	v_exp_f32_e32 v0, v0
	s_nop 0
	v_mul_f32_e32 v177, v170, v0
	v_pk_mul_f32 v[132:133], v[96:97], v[0:1] op_sel_hi:[1,0]
	v_pk_mul_f32 v[130:131], v[94:95], v[0:1] op_sel_hi:[1,0]
	v_pk_mul_f32 v[136:137], v[92:93], v[0:1] op_sel_hi:[1,0]
	v_pk_mul_f32 v[134:135], v[90:91], v[0:1] op_sel_hi:[1,0]
	v_pk_mul_f32 v[140:141], v[88:89], v[0:1] op_sel_hi:[1,0]
	v_pk_mul_f32 v[138:139], v[86:87], v[0:1] op_sel_hi:[1,0]
	v_pk_mul_f32 v[144:145], v[84:85], v[0:1] op_sel_hi:[1,0]
	v_pk_mul_f32 v[142:143], v[82:83], v[0:1] op_sel_hi:[1,0]
	v_pk_mul_f32 v[148:149], v[80:81], v[0:1] op_sel_hi:[1,0]
	v_pk_mul_f32 v[146:147], v[78:79], v[0:1] op_sel_hi:[1,0]
	v_pk_mul_f32 v[152:153], v[76:77], v[0:1] op_sel_hi:[1,0]
	v_pk_mul_f32 v[150:151], v[74:75], v[0:1] op_sel_hi:[1,0]
	v_pk_mul_f32 v[156:157], v[72:73], v[0:1] op_sel_hi:[1,0]
	v_pk_mul_f32 v[154:155], v[70:71], v[0:1] op_sel_hi:[1,0]
	v_pk_mul_f32 v[160:161], v[68:69], v[0:1] op_sel_hi:[1,0]
	v_pk_mul_f32 v[158:159], v[66:67], v[0:1] op_sel_hi:[1,0]
